# SwiGLU epilogue rewritten with plain (non-packed) f32 ops grouped by 8 so no trans-hazard nops are needed
# speedup vs baseline: 1.0059x; 1.0059x over previous
.LBB0_216:
	v_lshl_add_u32 v181, s1, 8, v154
	v_lshl_or_b32 v170, s0, 7, v156
	v_readlane_b32 s0, v254, 45
	v_readlane_b32 s1, v254, 46
	s_movk_i32 s3, 0x1600
	s_mov_b32 s66, 0xbfb8aa3b
	s_mov_b64 s[68:69], 0x16000
	s_mov_b64 s[70:71], 0x6e000
	s_andn2_b64 vcc, exec, s[42:43]
	s_mov_b64 s[16:17], -1
	v_ashrrev_i32_e32 v171, 31, v170
	v_mov_b64_e32 v[152:153], s[0:1]
	v_lshlrev_b64 v[170:171], 1, v[170:171]
	v_mad_i64_i32 v[182:183], s[0:1], v181, s3, v[152:153]
	s_nop 0
	v_lshl_add_u64 v[182:183], v[182:183], 0, v[170:171]
	v_mul_f32_e32 v152, s66, v124
	v_mul_f32_e32 v153, s66, v125
	v_mul_f32_e32 v178, s66, v126
	v_mul_f32_e32 v179, s66, v127
	v_mul_f32_e32 v246, s66, v120
	v_mul_f32_e32 v247, s66, v121
	v_mul_f32_e32 v248, s66, v122
	v_mul_f32_e32 v249, s66, v123
	v_exp_f32_e32 v152, v152
	v_exp_f32_e32 v153, v153
	v_exp_f32_e32 v178, v178
	v_exp_f32_e32 v179, v179
	v_exp_f32_e32 v246, v246
	v_exp_f32_e32 v247, v247
	v_exp_f32_e32 v248, v248
	v_exp_f32_e32 v249, v249
	v_mul_f32_e32 v124, v124, v116
	v_mul_f32_e32 v125, v125, v117
	v_mul_f32_e32 v126, v126, v118
	v_mul_f32_e32 v127, v127, v119
	v_mul_f32_e32 v120, v120, v112
	v_mul_f32_e32 v121, v121, v113
	v_mul_f32_e32 v122, v122, v114
	v_mul_f32_e32 v123, v123, v115
	v_add_f32_e32 v152, 1.0, v152
	v_add_f32_e32 v153, 1.0, v153
	v_add_f32_e32 v178, 1.0, v178
	v_add_f32_e32 v179, 1.0, v179
	v_add_f32_e32 v246, 1.0, v246
	v_add_f32_e32 v247, 1.0, v247
	v_add_f32_e32 v248, 1.0, v248
	v_add_f32_e32 v249, 1.0, v249
	v_rcp_f32_e32 v152, v152
	v_rcp_f32_e32 v153, v153
	v_rcp_f32_e32 v178, v178
	v_rcp_f32_e32 v179, v179
	v_rcp_f32_e32 v246, v246
	v_rcp_f32_e32 v247, v247
	v_rcp_f32_e32 v248, v248
	v_rcp_f32_e32 v249, v249
	v_mul_f32_e32 v124, v124, v152
	v_mul_f32_e32 v125, v125, v153
	v_mul_f32_e32 v126, v126, v178
	v_mul_f32_e32 v127, v127, v179
	v_mul_f32_e32 v120, v120, v246
	v_mul_f32_e32 v121, v121, v247
	v_mul_f32_e32 v122, v122, v248
	v_mul_f32_e32 v123, v123, v249
	v_cvt_pk_bf16_f32 v116, v124, v125
	v_cvt_pk_bf16_f32 v117, v126, v127
	v_cvt_pk_bf16_f32 v118, v120, v121
	v_cvt_pk_bf16_f32 v119, v122, v123
	global_store_dwordx4 v[182:183], v[116:119], off
	v_mul_f32_e32 v152, s66, v108
	v_mul_f32_e32 v153, s66, v109
	v_mul_f32_e32 v178, s66, v110
	v_mul_f32_e32 v179, s66, v111
	v_mul_f32_e32 v246, s66, v104
	v_mul_f32_e32 v247, s66, v105
	v_mul_f32_e32 v248, s66, v106
	v_mul_f32_e32 v249, s66, v107
	v_exp_f32_e32 v152, v152
	v_exp_f32_e32 v153, v153
	v_exp_f32_e32 v178, v178
	v_exp_f32_e32 v179, v179
	v_exp_f32_e32 v246, v246
	v_exp_f32_e32 v247, v247
	v_exp_f32_e32 v248, v248
	v_exp_f32_e32 v249, v249
	v_mul_f32_e32 v108, v108, v100
	v_mul_f32_e32 v109, v109, v101
	v_mul_f32_e32 v110, v110, v102
	v_mul_f32_e32 v111, v111, v103
	v_mul_f32_e32 v104, v104, v96
	v_mul_f32_e32 v105, v105, v97
	v_mul_f32_e32 v106, v106, v98
	v_mul_f32_e32 v107, v107, v99
	v_add_f32_e32 v152, 1.0, v152
	v_add_f32_e32 v153, 1.0, v153
	v_add_f32_e32 v178, 1.0, v178
	v_add_f32_e32 v179, 1.0, v179
	v_add_f32_e32 v246, 1.0, v246
	v_add_f32_e32 v247, 1.0, v247
	v_add_f32_e32 v248, 1.0, v248
	v_add_f32_e32 v249, 1.0, v249
	v_rcp_f32_e32 v152, v152
	v_rcp_f32_e32 v153, v153
	v_rcp_f32_e32 v178, v178
	v_rcp_f32_e32 v179, v179
	v_rcp_f32_e32 v246, v246
	v_rcp_f32_e32 v247, v247
	v_rcp_f32_e32 v248, v248
	v_rcp_f32_e32 v249, v249
	v_mul_f32_e32 v108, v108, v152
	v_mul_f32_e32 v109, v109, v153
	v_mul_f32_e32 v110, v110, v178
	v_mul_f32_e32 v111, v111, v179
	v_mul_f32_e32 v104, v104, v246
	v_mul_f32_e32 v105, v105, v247
	v_mul_f32_e32 v106, v106, v248
	v_mul_f32_e32 v107, v107, v249
	v_cvt_pk_bf16_f32 v100, v108, v109
	v_cvt_pk_bf16_f32 v101, v110, v111
	v_cvt_pk_bf16_f32 v102, v104, v105
	v_cvt_pk_bf16_f32 v103, v106, v107
	v_lshl_add_u64 v[182:183], v[182:183], 0, s[68:69]
	s_nop 0
	global_store_dwordx4 v[182:183], v[100:103], off
	v_mul_f32_e32 v152, s66, v92
	v_mul_f32_e32 v153, s66, v93
	v_mul_f32_e32 v178, s66, v94
	v_mul_f32_e32 v179, s66, v95
	v_mul_f32_e32 v246, s66, v88
	v_mul_f32_e32 v247, s66, v89
	v_mul_f32_e32 v248, s66, v90
	v_mul_f32_e32 v249, s66, v91
	v_exp_f32_e32 v152, v152
	v_exp_f32_e32 v153, v153
	v_exp_f32_e32 v178, v178
	v_exp_f32_e32 v179, v179
	v_exp_f32_e32 v246, v246
	v_exp_f32_e32 v247, v247
	v_exp_f32_e32 v248, v248
	v_exp_f32_e32 v249, v249
	v_mul_f32_e32 v92, v92, v84
	v_mul_f32_e32 v93, v93, v85
	v_mul_f32_e32 v94, v94, v86
	v_mul_f32_e32 v95, v95, v87
	v_mul_f32_e32 v88, v88, v80
	v_mul_f32_e32 v89, v89, v81
	v_mul_f32_e32 v90, v90, v82
	v_mul_f32_e32 v91, v91, v83
	v_add_f32_e32 v152, 1.0, v152
	v_add_f32_e32 v153, 1.0, v153
	v_add_f32_e32 v178, 1.0, v178
	v_add_f32_e32 v179, 1.0, v179
	v_add_f32_e32 v246, 1.0, v246
	v_add_f32_e32 v247, 1.0, v247
	v_add_f32_e32 v248, 1.0, v248
	v_add_f32_e32 v249, 1.0, v249
	v_rcp_f32_e32 v152, v152
	v_rcp_f32_e32 v153, v153
	v_rcp_f32_e32 v178, v178
	v_rcp_f32_e32 v179, v179
	v_rcp_f32_e32 v246, v246
	v_rcp_f32_e32 v247, v247
	v_rcp_f32_e32 v248, v248
	v_rcp_f32_e32 v249, v249
	v_mul_f32_e32 v92, v92, v152
	v_mul_f32_e32 v93, v93, v153
	v_mul_f32_e32 v94, v94, v178
	v_mul_f32_e32 v95, v95, v179
	v_mul_f32_e32 v88, v88, v246
	v_mul_f32_e32 v89, v89, v247
	v_mul_f32_e32 v90, v90, v248
	v_mul_f32_e32 v91, v91, v249
	v_cvt_pk_bf16_f32 v84, v92, v93
	v_cvt_pk_bf16_f32 v85, v94, v95
	v_cvt_pk_bf16_f32 v86, v88, v89
	v_cvt_pk_bf16_f32 v87, v90, v91
	v_lshl_add_u64 v[182:183], v[182:183], 0, s[68:69]
	s_nop 0
	global_store_dwordx4 v[182:183], v[84:87], off
	v_mul_f32_e32 v152, s66, v76
	v_mul_f32_e32 v153, s66, v77
	v_mul_f32_e32 v178, s66, v78
	v_mul_f32_e32 v179, s66, v79
	v_mul_f32_e32 v246, s66, v72
	v_mul_f32_e32 v247, s66, v73
	v_mul_f32_e32 v248, s66, v74
	v_mul_f32_e32 v249, s66, v75
	v_exp_f32_e32 v152, v152
	v_exp_f32_e32 v153, v153
	v_exp_f32_e32 v178, v178
	v_exp_f32_e32 v179, v179
	v_exp_f32_e32 v246, v246
	v_exp_f32_e32 v247, v247
	v_exp_f32_e32 v248, v248
	v_exp_f32_e32 v249, v249
	v_mul_f32_e32 v76, v76, v68
	v_mul_f32_e32 v77, v77, v69
	v_mul_f32_e32 v78, v78, v70
	v_mul_f32_e32 v79, v79, v71
	v_mul_f32_e32 v72, v72, v64
	v_mul_f32_e32 v73, v73, v65
	v_mul_f32_e32 v74, v74, v66
	v_mul_f32_e32 v75, v75, v67
	v_add_f32_e32 v152, 1.0, v152
	v_add_f32_e32 v153, 1.0, v153
	v_add_f32_e32 v178, 1.0, v178
	v_add_f32_e32 v179, 1.0, v179
	v_add_f32_e32 v246, 1.0, v246
	v_add_f32_e32 v247, 1.0, v247
	v_add_f32_e32 v248, 1.0, v248
	v_add_f32_e32 v249, 1.0, v249
	v_rcp_f32_e32 v152, v152
	v_rcp_f32_e32 v153, v153
	v_rcp_f32_e32 v178, v178
	v_rcp_f32_e32 v179, v179
	v_rcp_f32_e32 v246, v246
	v_rcp_f32_e32 v247, v247
	v_rcp_f32_e32 v248, v248
	v_rcp_f32_e32 v249, v249
	v_mul_f32_e32 v76, v76, v152
	v_mul_f32_e32 v77, v77, v153
	v_mul_f32_e32 v78, v78, v178
	v_mul_f32_e32 v79, v79, v179
	v_mul_f32_e32 v72, v72, v246
	v_mul_f32_e32 v73, v73, v247
	v_mul_f32_e32 v74, v74, v248
	v_mul_f32_e32 v75, v75, v249
	v_cvt_pk_bf16_f32 v68, v76, v77
	v_cvt_pk_bf16_f32 v69, v78, v79
	v_cvt_pk_bf16_f32 v70, v72, v73
	v_cvt_pk_bf16_f32 v71, v74, v75
	v_lshl_add_u64 v[182:183], v[182:183], 0, s[68:69]
	s_nop 0
	global_store_dwordx4 v[182:183], v[68:71], off
	v_mul_f32_e32 v152, s66, v60
	v_mul_f32_e32 v153, s66, v61
	v_mul_f32_e32 v178, s66, v62
	v_mul_f32_e32 v179, s66, v63
	v_mul_f32_e32 v246, s66, v56
	v_mul_f32_e32 v247, s66, v57
	v_mul_f32_e32 v248, s66, v58
	v_mul_f32_e32 v249, s66, v59
	v_exp_f32_e32 v152, v152
	v_exp_f32_e32 v153, v153
	v_exp_f32_e32 v178, v178
	v_exp_f32_e32 v179, v179
	v_exp_f32_e32 v246, v246
	v_exp_f32_e32 v247, v247
	v_exp_f32_e32 v248, v248
	v_exp_f32_e32 v249, v249
	v_mul_f32_e32 v60, v60, v52
	v_mul_f32_e32 v61, v61, v53
	v_mul_f32_e32 v62, v62, v54
	v_mul_f32_e32 v63, v63, v55
	v_mul_f32_e32 v56, v56, v48
	v_mul_f32_e32 v57, v57, v49
	v_mul_f32_e32 v58, v58, v50
	v_mul_f32_e32 v59, v59, v51
	v_add_f32_e32 v152, 1.0, v152
	v_add_f32_e32 v153, 1.0, v153
	v_add_f32_e32 v178, 1.0, v178
	v_add_f32_e32 v179, 1.0, v179
	v_add_f32_e32 v246, 1.0, v246
	v_add_f32_e32 v247, 1.0, v247
	v_add_f32_e32 v248, 1.0, v248
	v_add_f32_e32 v249, 1.0, v249
	v_rcp_f32_e32 v152, v152
	v_rcp_f32_e32 v153, v153
	v_rcp_f32_e32 v178, v178
	v_rcp_f32_e32 v179, v179
	v_rcp_f32_e32 v246, v246
	v_rcp_f32_e32 v247, v247
	v_rcp_f32_e32 v248, v248
	v_rcp_f32_e32 v249, v249
	v_mul_f32_e32 v60, v60, v152
	v_mul_f32_e32 v61, v61, v153
	v_mul_f32_e32 v62, v62, v178
	v_mul_f32_e32 v63, v63, v179
	v_mul_f32_e32 v56, v56, v246
	v_mul_f32_e32 v57, v57, v247
	v_mul_f32_e32 v58, v58, v248
	v_mul_f32_e32 v59, v59, v249
	v_cvt_pk_bf16_f32 v52, v60, v61
	v_cvt_pk_bf16_f32 v53, v62, v63
	v_cvt_pk_bf16_f32 v54, v56, v57
	v_cvt_pk_bf16_f32 v55, v58, v59
	v_lshl_add_u64 v[182:183], v[182:183], 0, s[70:71]
	s_nop 0
	global_store_dwordx4 v[182:183], v[52:55], off
	v_mul_f32_e32 v152, s66, v44
	v_mul_f32_e32 v153, s66, v45
	v_mul_f32_e32 v178, s66, v46
	v_mul_f32_e32 v179, s66, v47
	v_mul_f32_e32 v246, s66, v40
	v_mul_f32_e32 v247, s66, v41
	v_mul_f32_e32 v248, s66, v42
	v_mul_f32_e32 v249, s66, v43
	v_exp_f32_e32 v152, v152
	v_exp_f32_e32 v153, v153
	v_exp_f32_e32 v178, v178
	v_exp_f32_e32 v179, v179
	v_exp_f32_e32 v246, v246
	v_exp_f32_e32 v247, v247
	v_exp_f32_e32 v248, v248
	v_exp_f32_e32 v249, v249
	v_mul_f32_e32 v44, v44, v36
	v_mul_f32_e32 v45, v45, v37
	v_mul_f32_e32 v46, v46, v38
	v_mul_f32_e32 v47, v47, v39
	v_mul_f32_e32 v40, v40, v32
	v_mul_f32_e32 v41, v41, v33
	v_mul_f32_e32 v42, v42, v34
	v_mul_f32_e32 v43, v43, v35
	v_add_f32_e32 v152, 1.0, v152
	v_add_f32_e32 v153, 1.0, v153
	v_add_f32_e32 v178, 1.0, v178
	v_add_f32_e32 v179, 1.0, v179
	v_add_f32_e32 v246, 1.0, v246
	v_add_f32_e32 v247, 1.0, v247
	v_add_f32_e32 v248, 1.0, v248
	v_add_f32_e32 v249, 1.0, v249
	v_rcp_f32_e32 v152, v152
	v_rcp_f32_e32 v153, v153
	v_rcp_f32_e32 v178, v178
	v_rcp_f32_e32 v179, v179
	v_rcp_f32_e32 v246, v246
	v_rcp_f32_e32 v247, v247
	v_rcp_f32_e32 v248, v248
	v_rcp_f32_e32 v249, v249
	v_mul_f32_e32 v44, v44, v152
	v_mul_f32_e32 v45, v45, v153
	v_mul_f32_e32 v46, v46, v178
	v_mul_f32_e32 v47, v47, v179
	v_mul_f32_e32 v40, v40, v246
	v_mul_f32_e32 v41, v41, v247
	v_mul_f32_e32 v42, v42, v248
	v_mul_f32_e32 v43, v43, v249
	v_cvt_pk_bf16_f32 v36, v44, v45
	v_cvt_pk_bf16_f32 v37, v46, v47
	v_cvt_pk_bf16_f32 v38, v40, v41
	v_cvt_pk_bf16_f32 v39, v42, v43
	v_lshl_add_u64 v[182:183], v[182:183], 0, s[68:69]
	s_nop 0
	global_store_dwordx4 v[182:183], v[36:39], off
	v_mul_f32_e32 v152, s66, v28
	v_mul_f32_e32 v153, s66, v29
	v_mul_f32_e32 v178, s66, v30
	v_mul_f32_e32 v179, s66, v31
	v_mul_f32_e32 v246, s66, v24
	v_mul_f32_e32 v247, s66, v25
	v_mul_f32_e32 v248, s66, v26
	v_mul_f32_e32 v249, s66, v27
	v_exp_f32_e32 v152, v152
	v_exp_f32_e32 v153, v153
	v_exp_f32_e32 v178, v178
	v_exp_f32_e32 v179, v179
	v_exp_f32_e32 v246, v246
	v_exp_f32_e32 v247, v247
	v_exp_f32_e32 v248, v248
	v_exp_f32_e32 v249, v249
	v_mul_f32_e32 v28, v28, v20
	v_mul_f32_e32 v29, v29, v21
	v_mul_f32_e32 v30, v30, v22
	v_mul_f32_e32 v31, v31, v23
	v_mul_f32_e32 v24, v24, v16
	v_mul_f32_e32 v25, v25, v17
	v_mul_f32_e32 v26, v26, v18
	v_mul_f32_e32 v27, v27, v19
	v_add_f32_e32 v152, 1.0, v152
	v_add_f32_e32 v153, 1.0, v153
	v_add_f32_e32 v178, 1.0, v178
	v_add_f32_e32 v179, 1.0, v179
	v_add_f32_e32 v246, 1.0, v246
	v_add_f32_e32 v247, 1.0, v247
	v_add_f32_e32 v248, 1.0, v248
	v_add_f32_e32 v249, 1.0, v249
	v_rcp_f32_e32 v152, v152
	v_rcp_f32_e32 v153, v153
	v_rcp_f32_e32 v178, v178
	v_rcp_f32_e32 v179, v179
	v_rcp_f32_e32 v246, v246
	v_rcp_f32_e32 v247, v247
	v_rcp_f32_e32 v248, v248
	v_rcp_f32_e32 v249, v249
	v_mul_f32_e32 v28, v28, v152
	v_mul_f32_e32 v29, v29, v153
	v_mul_f32_e32 v30, v30, v178
	v_mul_f32_e32 v31, v31, v179
	v_mul_f32_e32 v24, v24, v246
	v_mul_f32_e32 v25, v25, v247
	v_mul_f32_e32 v26, v26, v248
	v_mul_f32_e32 v27, v27, v249
	v_cvt_pk_bf16_f32 v20, v28, v29
	v_cvt_pk_bf16_f32 v21, v30, v31
	v_cvt_pk_bf16_f32 v22, v24, v25
	v_cvt_pk_bf16_f32 v23, v26, v27
	v_lshl_add_u64 v[182:183], v[182:183], 0, s[68:69]
	s_nop 0
	global_store_dwordx4 v[182:183], v[20:23], off
	v_mul_f32_e32 v152, s66, v12
	v_mul_f32_e32 v153, s66, v13
	v_mul_f32_e32 v178, s66, v14
	v_mul_f32_e32 v179, s66, v15
	v_mul_f32_e32 v246, s66, v8
	v_mul_f32_e32 v247, s66, v9
	v_mul_f32_e32 v248, s66, v10
	v_mul_f32_e32 v249, s66, v11
	v_exp_f32_e32 v152, v152
	v_exp_f32_e32 v153, v153
	v_exp_f32_e32 v178, v178
	v_exp_f32_e32 v179, v179
	v_exp_f32_e32 v246, v246
	v_exp_f32_e32 v247, v247
	v_exp_f32_e32 v248, v248
	v_exp_f32_e32 v249, v249
	v_mul_f32_e32 v12, v12, v4
	v_mul_f32_e32 v13, v13, v5
	v_mul_f32_e32 v14, v14, v6
	v_mul_f32_e32 v15, v15, v7
	v_mul_f32_e32 v8, v8, v0
	v_mul_f32_e32 v9, v9, v1
	v_mul_f32_e32 v10, v10, v2
	v_mul_f32_e32 v11, v11, v3
	v_add_f32_e32 v152, 1.0, v152
	v_add_f32_e32 v153, 1.0, v153
	v_add_f32_e32 v178, 1.0, v178
	v_add_f32_e32 v179, 1.0, v179
	v_add_f32_e32 v246, 1.0, v246
	v_add_f32_e32 v247, 1.0, v247
	v_add_f32_e32 v248, 1.0, v248
	v_add_f32_e32 v249, 1.0, v249
	v_rcp_f32_e32 v152, v152
	v_rcp_f32_e32 v153, v153
	v_rcp_f32_e32 v178, v178
	v_rcp_f32_e32 v179, v179
	v_rcp_f32_e32 v246, v246
	v_rcp_f32_e32 v247, v247
	v_rcp_f32_e32 v248, v248
	v_rcp_f32_e32 v249, v249
	v_mul_f32_e32 v12, v12, v152
	v_mul_f32_e32 v13, v13, v153
	v_mul_f32_e32 v14, v14, v178
	v_mul_f32_e32 v15, v15, v179
	v_mul_f32_e32 v8, v8, v246
	v_mul_f32_e32 v9, v9, v247
	v_mul_f32_e32 v10, v10, v248
	v_mul_f32_e32 v11, v11, v249
	v_cvt_pk_bf16_f32 v4, v12, v13
	v_cvt_pk_bf16_f32 v5, v14, v15
	v_cvt_pk_bf16_f32 v6, v8, v9
	v_cvt_pk_bf16_f32 v7, v10, v11
	v_lshl_add_u64 v[182:183], v[182:183], 0, s[68:69]
	s_nop 0
	global_store_dwordx4 v[182:183], v[4:7], off
	s_cbranch_vccnz .LBB0_209
	s_andn2_b64 vcc, exec, s[4:5]
	s_cbranch_vccnz .LBB0_208
	s_barrier
	s_branch .LBB0_208

.LBB0_1441:
	v_lshl_add_u32 v181, s1, 8, v154
	v_lshl_or_b32 v170, s0, 7, v156
	v_readlane_b32 s0, v254, 45
	v_readlane_b32 s1, v254, 46
	s_movk_i32 s3, 0x1600
	s_mov_b32 s66, 0xbfb8aa3b
	s_mov_b64 s[68:69], 0x16000
	s_mov_b64 s[70:71], 0x6e000
	s_andn2_b64 vcc, exec, s[40:41]
	s_mov_b64 s[16:17], -1
	v_ashrrev_i32_e32 v171, 31, v170
	v_mov_b64_e32 v[152:153], s[0:1]
	v_lshlrev_b64 v[170:171], 1, v[170:171]
	v_mad_i64_i32 v[182:183], s[0:1], v181, s3, v[152:153]
	s_nop 0
	v_lshl_add_u64 v[182:183], v[182:183], 0, v[170:171]
	v_mul_f32_e32 v152, s66, v124
	v_mul_f32_e32 v153, s66, v125
	v_mul_f32_e32 v178, s66, v126
	v_mul_f32_e32 v179, s66, v127
	v_mul_f32_e32 v246, s66, v120
	v_mul_f32_e32 v247, s66, v121
	v_mul_f32_e32 v248, s66, v122
	v_mul_f32_e32 v249, s66, v123
	v_exp_f32_e32 v152, v152
	v_exp_f32_e32 v153, v153
	v_exp_f32_e32 v178, v178
	v_exp_f32_e32 v179, v179
	v_exp_f32_e32 v246, v246
	v_exp_f32_e32 v247, v247
	v_exp_f32_e32 v248, v248
	v_exp_f32_e32 v249, v249
	v_mul_f32_e32 v124, v124, v116
	v_mul_f32_e32 v125, v125, v117
	v_mul_f32_e32 v126, v126, v118
	v_mul_f32_e32 v127, v127, v119
	v_mul_f32_e32 v120, v120, v112
	v_mul_f32_e32 v121, v121, v113
	v_mul_f32_e32 v122, v122, v114
	v_mul_f32_e32 v123, v123, v115
	v_add_f32_e32 v152, 1.0, v152
	v_add_f32_e32 v153, 1.0, v153
	v_add_f32_e32 v178, 1.0, v178
	v_add_f32_e32 v179, 1.0, v179
	v_add_f32_e32 v246, 1.0, v246
	v_add_f32_e32 v247, 1.0, v247
	v_add_f32_e32 v248, 1.0, v248
	v_add_f32_e32 v249, 1.0, v249
	v_rcp_f32_e32 v152, v152
	v_rcp_f32_e32 v153, v153
	v_rcp_f32_e32 v178, v178
	v_rcp_f32_e32 v179, v179
	v_rcp_f32_e32 v246, v246
	v_rcp_f32_e32 v247, v247
	v_rcp_f32_e32 v248, v248
	v_rcp_f32_e32 v249, v249
	v_mul_f32_e32 v124, v124, v152
	v_mul_f32_e32 v125, v125, v153
	v_mul_f32_e32 v126, v126, v178
	v_mul_f32_e32 v127, v127, v179
	v_mul_f32_e32 v120, v120, v246
	v_mul_f32_e32 v121, v121, v247
	v_mul_f32_e32 v122, v122, v248
	v_mul_f32_e32 v123, v123, v249
	v_cvt_pk_bf16_f32 v116, v124, v125
	v_cvt_pk_bf16_f32 v117, v126, v127
	v_cvt_pk_bf16_f32 v118, v120, v121
	v_cvt_pk_bf16_f32 v119, v122, v123
	global_store_dwordx4 v[182:183], v[116:119], off
	v_mul_f32_e32 v152, s66, v108
	v_mul_f32_e32 v153, s66, v109
	v_mul_f32_e32 v178, s66, v110
	v_mul_f32_e32 v179, s66, v111
	v_mul_f32_e32 v246, s66, v104
	v_mul_f32_e32 v247, s66, v105
	v_mul_f32_e32 v248, s66, v106
	v_mul_f32_e32 v249, s66, v107
	v_exp_f32_e32 v152, v152
	v_exp_f32_e32 v153, v153
	v_exp_f32_e32 v178, v178
	v_exp_f32_e32 v179, v179
	v_exp_f32_e32 v246, v246
	v_exp_f32_e32 v247, v247
	v_exp_f32_e32 v248, v248
	v_exp_f32_e32 v249, v249
	v_mul_f32_e32 v108, v108, v100
	v_mul_f32_e32 v109, v109, v101
	v_mul_f32_e32 v110, v110, v102
	v_mul_f32_e32 v111, v111, v103
	v_mul_f32_e32 v104, v104, v96
	v_mul_f32_e32 v105, v105, v97
	v_mul_f32_e32 v106, v106, v98
	v_mul_f32_e32 v107, v107, v99
	v_add_f32_e32 v152, 1.0, v152
	v_add_f32_e32 v153, 1.0, v153
	v_add_f32_e32 v178, 1.0, v178
	v_add_f32_e32 v179, 1.0, v179
	v_add_f32_e32 v246, 1.0, v246
	v_add_f32_e32 v247, 1.0, v247
	v_add_f32_e32 v248, 1.0, v248
	v_add_f32_e32 v249, 1.0, v249
	v_rcp_f32_e32 v152, v152
	v_rcp_f32_e32 v153, v153
	v_rcp_f32_e32 v178, v178
	v_rcp_f32_e32 v179, v179
	v_rcp_f32_e32 v246, v246
	v_rcp_f32_e32 v247, v247
	v_rcp_f32_e32 v248, v248
	v_rcp_f32_e32 v249, v249
	v_mul_f32_e32 v108, v108, v152
	v_mul_f32_e32 v109, v109, v153
	v_mul_f32_e32 v110, v110, v178
	v_mul_f32_e32 v111, v111, v179
	v_mul_f32_e32 v104, v104, v246
	v_mul_f32_e32 v105, v105, v247
	v_mul_f32_e32 v106, v106, v248
	v_mul_f32_e32 v107, v107, v249
	v_cvt_pk_bf16_f32 v100, v108, v109
	v_cvt_pk_bf16_f32 v101, v110, v111
	v_cvt_pk_bf16_f32 v102, v104, v105
	v_cvt_pk_bf16_f32 v103, v106, v107
	v_lshl_add_u64 v[182:183], v[182:183], 0, s[68:69]
	s_nop 0
	global_store_dwordx4 v[182:183], v[100:103], off
	v_mul_f32_e32 v152, s66, v92
	v_mul_f32_e32 v153, s66, v93
	v_mul_f32_e32 v178, s66, v94
	v_mul_f32_e32 v179, s66, v95
	v_mul_f32_e32 v246, s66, v88
	v_mul_f32_e32 v247, s66, v89
	v_mul_f32_e32 v248, s66, v90
	v_mul_f32_e32 v249, s66, v91
	v_exp_f32_e32 v152, v152
	v_exp_f32_e32 v153, v153
	v_exp_f32_e32 v178, v178
	v_exp_f32_e32 v179, v179
	v_exp_f32_e32 v246, v246
	v_exp_f32_e32 v247, v247
	v_exp_f32_e32 v248, v248
	v_exp_f32_e32 v249, v249
	v_mul_f32_e32 v92, v92, v84
	v_mul_f32_e32 v93, v93, v85
	v_mul_f32_e32 v94, v94, v86
	v_mul_f32_e32 v95, v95, v87
	v_mul_f32_e32 v88, v88, v80
	v_mul_f32_e32 v89, v89, v81
	v_mul_f32_e32 v90, v90, v82
	v_mul_f32_e32 v91, v91, v83
	v_add_f32_e32 v152, 1.0, v152
	v_add_f32_e32 v153, 1.0, v153
	v_add_f32_e32 v178, 1.0, v178
	v_add_f32_e32 v179, 1.0, v179
	v_add_f32_e32 v246, 1.0, v246
	v_add_f32_e32 v247, 1.0, v247
	v_add_f32_e32 v248, 1.0, v248
	v_add_f32_e32 v249, 1.0, v249
	v_rcp_f32_e32 v152, v152
	v_rcp_f32_e32 v153, v153
	v_rcp_f32_e32 v178, v178
	v_rcp_f32_e32 v179, v179
	v_rcp_f32_e32 v246, v246
	v_rcp_f32_e32 v247, v247
	v_rcp_f32_e32 v248, v248
	v_rcp_f32_e32 v249, v249
	v_mul_f32_e32 v92, v92, v152
	v_mul_f32_e32 v93, v93, v153
	v_mul_f32_e32 v94, v94, v178
	v_mul_f32_e32 v95, v95, v179
	v_mul_f32_e32 v88, v88, v246
	v_mul_f32_e32 v89, v89, v247
	v_mul_f32_e32 v90, v90, v248
	v_mul_f32_e32 v91, v91, v249
	v_cvt_pk_bf16_f32 v84, v92, v93
	v_cvt_pk_bf16_f32 v85, v94, v95
	v_cvt_pk_bf16_f32 v86, v88, v89
	v_cvt_pk_bf16_f32 v87, v90, v91
	v_lshl_add_u64 v[182:183], v[182:183], 0, s[68:69]
	s_nop 0
	global_store_dwordx4 v[182:183], v[84:87], off
	v_mul_f32_e32 v152, s66, v76
	v_mul_f32_e32 v153, s66, v77
	v_mul_f32_e32 v178, s66, v78
	v_mul_f32_e32 v179, s66, v79
	v_mul_f32_e32 v246, s66, v72
	v_mul_f32_e32 v247, s66, v73
	v_mul_f32_e32 v248, s66, v74
	v_mul_f32_e32 v249, s66, v75
	v_exp_f32_e32 v152, v152
	v_exp_f32_e32 v153, v153
	v_exp_f32_e32 v178, v178
	v_exp_f32_e32 v179, v179
	v_exp_f32_e32 v246, v246
	v_exp_f32_e32 v247, v247
	v_exp_f32_e32 v248, v248
	v_exp_f32_e32 v249, v249
	v_mul_f32_e32 v76, v76, v68
	v_mul_f32_e32 v77, v77, v69
	v_mul_f32_e32 v78, v78, v70
	v_mul_f32_e32 v79, v79, v71
	v_mul_f32_e32 v72, v72, v64
	v_mul_f32_e32 v73, v73, v65
	v_mul_f32_e32 v74, v74, v66
	v_mul_f32_e32 v75, v75, v67
	v_add_f32_e32 v152, 1.0, v152
	v_add_f32_e32 v153, 1.0, v153
	v_add_f32_e32 v178, 1.0, v178
	v_add_f32_e32 v179, 1.0, v179
	v_add_f32_e32 v246, 1.0, v246
	v_add_f32_e32 v247, 1.0, v247
	v_add_f32_e32 v248, 1.0, v248
	v_add_f32_e32 v249, 1.0, v249
	v_rcp_f32_e32 v152, v152
	v_rcp_f32_e32 v153, v153
	v_rcp_f32_e32 v178, v178
	v_rcp_f32_e32 v179, v179
	v_rcp_f32_e32 v246, v246
	v_rcp_f32_e32 v247, v247
	v_rcp_f32_e32 v248, v248
	v_rcp_f32_e32 v249, v249
	v_mul_f32_e32 v76, v76, v152
	v_mul_f32_e32 v77, v77, v153
	v_mul_f32_e32 v78, v78, v178
	v_mul_f32_e32 v79, v79, v179
	v_mul_f32_e32 v72, v72, v246
	v_mul_f32_e32 v73, v73, v247
	v_mul_f32_e32 v74, v74, v248
	v_mul_f32_e32 v75, v75, v249
	v_cvt_pk_bf16_f32 v68, v76, v77
	v_cvt_pk_bf16_f32 v69, v78, v79
	v_cvt_pk_bf16_f32 v70, v72, v73
	v_cvt_pk_bf16_f32 v71, v74, v75
	v_lshl_add_u64 v[182:183], v[182:183], 0, s[68:69]
	s_nop 0
	global_store_dwordx4 v[182:183], v[68:71], off
	v_mul_f32_e32 v152, s66, v60
	v_mul_f32_e32 v153, s66, v61
	v_mul_f32_e32 v178, s66, v62
	v_mul_f32_e32 v179, s66, v63
	v_mul_f32_e32 v246, s66, v56
	v_mul_f32_e32 v247, s66, v57
	v_mul_f32_e32 v248, s66, v58
	v_mul_f32_e32 v249, s66, v59
	v_exp_f32_e32 v152, v152
	v_exp_f32_e32 v153, v153
	v_exp_f32_e32 v178, v178
	v_exp_f32_e32 v179, v179
	v_exp_f32_e32 v246, v246
	v_exp_f32_e32 v247, v247
	v_exp_f32_e32 v248, v248
	v_exp_f32_e32 v249, v249
	v_mul_f32_e32 v60, v60, v52
	v_mul_f32_e32 v61, v61, v53
	v_mul_f32_e32 v62, v62, v54
	v_mul_f32_e32 v63, v63, v55
	v_mul_f32_e32 v56, v56, v48
	v_mul_f32_e32 v57, v57, v49
	v_mul_f32_e32 v58, v58, v50
	v_mul_f32_e32 v59, v59, v51
	v_add_f32_e32 v152, 1.0, v152
	v_add_f32_e32 v153, 1.0, v153
	v_add_f32_e32 v178, 1.0, v178
	v_add_f32_e32 v179, 1.0, v179
	v_add_f32_e32 v246, 1.0, v246
	v_add_f32_e32 v247, 1.0, v247
	v_add_f32_e32 v248, 1.0, v248
	v_add_f32_e32 v249, 1.0, v249
	v_rcp_f32_e32 v152, v152
	v_rcp_f32_e32 v153, v153
	v_rcp_f32_e32 v178, v178
	v_rcp_f32_e32 v179, v179
	v_rcp_f32_e32 v246, v246
	v_rcp_f32_e32 v247, v247
	v_rcp_f32_e32 v248, v248
	v_rcp_f32_e32 v249, v249
	v_mul_f32_e32 v60, v60, v152
	v_mul_f32_e32 v61, v61, v153
	v_mul_f32_e32 v62, v62, v178
	v_mul_f32_e32 v63, v63, v179
	v_mul_f32_e32 v56, v56, v246
	v_mul_f32_e32 v57, v57, v247
	v_mul_f32_e32 v58, v58, v248
	v_mul_f32_e32 v59, v59, v249
	v_cvt_pk_bf16_f32 v52, v60, v61
	v_cvt_pk_bf16_f32 v53, v62, v63
	v_cvt_pk_bf16_f32 v54, v56, v57
	v_cvt_pk_bf16_f32 v55, v58, v59
	v_lshl_add_u64 v[182:183], v[182:183], 0, s[70:71]
	s_nop 0
	global_store_dwordx4 v[182:183], v[52:55], off
	v_mul_f32_e32 v152, s66, v44
	v_mul_f32_e32 v153, s66, v45
	v_mul_f32_e32 v178, s66, v46
	v_mul_f32_e32 v179, s66, v47
	v_mul_f32_e32 v246, s66, v40
	v_mul_f32_e32 v247, s66, v41
	v_mul_f32_e32 v248, s66, v42
	v_mul_f32_e32 v249, s66, v43
	v_exp_f32_e32 v152, v152
	v_exp_f32_e32 v153, v153
	v_exp_f32_e32 v178, v178
	v_exp_f32_e32 v179, v179
	v_exp_f32_e32 v246, v246
	v_exp_f32_e32 v247, v247
	v_exp_f32_e32 v248, v248
	v_exp_f32_e32 v249, v249
	v_mul_f32_e32 v44, v44, v36
	v_mul_f32_e32 v45, v45, v37
	v_mul_f32_e32 v46, v46, v38
	v_mul_f32_e32 v47, v47, v39
	v_mul_f32_e32 v40, v40, v32
	v_mul_f32_e32 v41, v41, v33
	v_mul_f32_e32 v42, v42, v34
	v_mul_f32_e32 v43, v43, v35
	v_add_f32_e32 v152, 1.0, v152
	v_add_f32_e32 v153, 1.0, v153
	v_add_f32_e32 v178, 1.0, v178
	v_add_f32_e32 v179, 1.0, v179
	v_add_f32_e32 v246, 1.0, v246
	v_add_f32_e32 v247, 1.0, v247
	v_add_f32_e32 v248, 1.0, v248
	v_add_f32_e32 v249, 1.0, v249
	v_rcp_f32_e32 v152, v152
	v_rcp_f32_e32 v153, v153
	v_rcp_f32_e32 v178, v178
	v_rcp_f32_e32 v179, v179
	v_rcp_f32_e32 v246, v246
	v_rcp_f32_e32 v247, v247
	v_rcp_f32_e32 v248, v248
	v_rcp_f32_e32 v249, v249
	v_mul_f32_e32 v44, v44, v152
	v_mul_f32_e32 v45, v45, v153
	v_mul_f32_e32 v46, v46, v178
	v_mul_f32_e32 v47, v47, v179
	v_mul_f32_e32 v40, v40, v246
	v_mul_f32_e32 v41, v41, v247
	v_mul_f32_e32 v42, v42, v248
	v_mul_f32_e32 v43, v43, v249
	v_cvt_pk_bf16_f32 v36, v44, v45
	v_cvt_pk_bf16_f32 v37, v46, v47
	v_cvt_pk_bf16_f32 v38, v40, v41
	v_cvt_pk_bf16_f32 v39, v42, v43
	v_lshl_add_u64 v[182:183], v[182:183], 0, s[68:69]
	s_nop 0
	global_store_dwordx4 v[182:183], v[36:39], off
	v_mul_f32_e32 v152, s66, v28
	v_mul_f32_e32 v153, s66, v29
	v_mul_f32_e32 v178, s66, v30
	v_mul_f32_e32 v179, s66, v31
	v_mul_f32_e32 v246, s66, v24
	v_mul_f32_e32 v247, s66, v25
	v_mul_f32_e32 v248, s66, v26
	v_mul_f32_e32 v249, s66, v27
	v_exp_f32_e32 v152, v152
	v_exp_f32_e32 v153, v153
	v_exp_f32_e32 v178, v178
	v_exp_f32_e32 v179, v179
	v_exp_f32_e32 v246, v246
	v_exp_f32_e32 v247, v247
	v_exp_f32_e32 v248, v248
	v_exp_f32_e32 v249, v249
	v_mul_f32_e32 v28, v28, v20
	v_mul_f32_e32 v29, v29, v21
	v_mul_f32_e32 v30, v30, v22
	v_mul_f32_e32 v31, v31, v23
	v_mul_f32_e32 v24, v24, v16
	v_mul_f32_e32 v25, v25, v17
	v_mul_f32_e32 v26, v26, v18
	v_mul_f32_e32 v27, v27, v19
	v_add_f32_e32 v152, 1.0, v152
	v_add_f32_e32 v153, 1.0, v153
	v_add_f32_e32 v178, 1.0, v178
	v_add_f32_e32 v179, 1.0, v179
	v_add_f32_e32 v246, 1.0, v246
	v_add_f32_e32 v247, 1.0, v247
	v_add_f32_e32 v248, 1.0, v248
	v_add_f32_e32 v249, 1.0, v249
	v_rcp_f32_e32 v152, v152
	v_rcp_f32_e32 v153, v153
	v_rcp_f32_e32 v178, v178
	v_rcp_f32_e32 v179, v179
	v_rcp_f32_e32 v246, v246
	v_rcp_f32_e32 v247, v247
	v_rcp_f32_e32 v248, v248
	v_rcp_f32_e32 v249, v249
	v_mul_f32_e32 v28, v28, v152
	v_mul_f32_e32 v29, v29, v153
	v_mul_f32_e32 v30, v30, v178
	v_mul_f32_e32 v31, v31, v179
	v_mul_f32_e32 v24, v24, v246
	v_mul_f32_e32 v25, v25, v247
	v_mul_f32_e32 v26, v26, v248
	v_mul_f32_e32 v27, v27, v249
	v_cvt_pk_bf16_f32 v20, v28, v29
	v_cvt_pk_bf16_f32 v21, v30, v31
	v_cvt_pk_bf16_f32 v22, v24, v25
	v_cvt_pk_bf16_f32 v23, v26, v27
	v_lshl_add_u64 v[182:183], v[182:183], 0, s[68:69]
	s_nop 0
	global_store_dwordx4 v[182:183], v[20:23], off
	v_mul_f32_e32 v152, s66, v12
	v_mul_f32_e32 v153, s66, v13
	v_mul_f32_e32 v178, s66, v14
	v_mul_f32_e32 v179, s66, v15
	v_mul_f32_e32 v246, s66, v8
	v_mul_f32_e32 v247, s66, v9
	v_mul_f32_e32 v248, s66, v10
	v_mul_f32_e32 v249, s66, v11
	v_exp_f32_e32 v152, v152
	v_exp_f32_e32 v153, v153
	v_exp_f32_e32 v178, v178
	v_exp_f32_e32 v179, v179
	v_exp_f32_e32 v246, v246
	v_exp_f32_e32 v247, v247
	v_exp_f32_e32 v248, v248
	v_exp_f32_e32 v249, v249
	v_mul_f32_e32 v12, v12, v4
	v_mul_f32_e32 v13, v13, v5
	v_mul_f32_e32 v14, v14, v6
	v_mul_f32_e32 v15, v15, v7
	v_mul_f32_e32 v8, v8, v0
	v_mul_f32_e32 v9, v9, v1
	v_mul_f32_e32 v10, v10, v2
	v_mul_f32_e32 v11, v11, v3
	v_add_f32_e32 v152, 1.0, v152
	v_add_f32_e32 v153, 1.0, v153
	v_add_f32_e32 v178, 1.0, v178
	v_add_f32_e32 v179, 1.0, v179
	v_add_f32_e32 v246, 1.0, v246
	v_add_f32_e32 v247, 1.0, v247
	v_add_f32_e32 v248, 1.0, v248
	v_add_f32_e32 v249, 1.0, v249
	v_rcp_f32_e32 v152, v152
	v_rcp_f32_e32 v153, v153
	v_rcp_f32_e32 v178, v178
	v_rcp_f32_e32 v179, v179
	v_rcp_f32_e32 v246, v246
	v_rcp_f32_e32 v247, v247
	v_rcp_f32_e32 v248, v248
	v_rcp_f32_e32 v249, v249
	v_mul_f32_e32 v12, v12, v152
	v_mul_f32_e32 v13, v13, v153
	v_mul_f32_e32 v14, v14, v178
	v_mul_f32_e32 v15, v15, v179
	v_mul_f32_e32 v8, v8, v246
	v_mul_f32_e32 v9, v9, v247
	v_mul_f32_e32 v10, v10, v248
	v_mul_f32_e32 v11, v11, v249
	v_cvt_pk_bf16_f32 v4, v12, v13
	v_cvt_pk_bf16_f32 v5, v14, v15
	v_cvt_pk_bf16_f32 v6, v8, v9
	v_cvt_pk_bf16_f32 v7, v10, v11
	v_lshl_add_u64 v[182:183], v[182:183], 0, s[68:69]
	s_nop 0
	global_store_dwordx4 v[182:183], v[4:7], off
	s_cbranch_vccnz .LBB0_1434
	s_andn2_b64 vcc, exec, s[4:5]
	s_cbranch_vccnz .LBB0_1433
	s_barrier
	s_branch .LBB0_1433
